# EpiGlu (P5): all 16 gate-activation loads issued up front into dead K-loop fragment VGPRs, copied per piece under counted vmcnt(15) (was load->vmcnt(0)->compute->store x16 serial)
# speedup vs baseline: 1.0002x; 1.0002x over previous
; #define EPI_OPAQUE(x) asm volatile("" : "+v"(x))
;     __device__ __forceinline__ void operator()(const f32x4 (&acc)[2][2][4][2], const Unit& u, int wr, int wc, int fr, int fq, const EpiCtx& X) const {
;         const bool odd = fr & 1; const int fe = fr - (fr & 1), o32 = (fr & 1) * 32;
;         const char* gb = (const char*)(GACT + (size_t)u.pm * BM * W_SSM + u.pn * BM);
;         unsigned glo = (unsigned)((wr * 64 + fe) * W_SSM + wc * 64 + o32 + 8 * fq) * 2u; EPI_OPAQUE(glo);
;         char* cb = (char*)(CC + (size_t)u.pm * BM * DM + u.pn * BM);
;         unsigned clo = (unsigned)((wr * 64 + fe) * DM + wc * 64 + o32 + 8 * fq) * 2u; EPI_OPAQUE(clo);
;     ...
;         EPI_PIECES({ const unsigned goff = glo + (unsigned)(rl * W_SSM) * 2u, coff = clo + (unsigned)(rl * DM) * 2u;
;             GLU_ONE(p1a, p1b, goff, coff); GLU_ONE(p2a, p2b, goff + W_SSM * 2, coff + DM * 2); })
.LBB0_502:
	s_ashr_i32 s27, s26, 31
	s_lshl_b64 s[24:25], s[26:27], 20
	s_add_u32 s17, s30, s24
	s_addc_u32 s19, s31, s25
	s_lshl_b32 s24, s35, 8
	s_ashr_i32 s25, s24, 31
	s_lshl_b64 s[54:55], s[24:25], 1
	s_add_u32 s24, s17, s54
	s_addc_u32 s25, s19, s55
	v_mov_b32_e32 v151, v145
	v_mov_b32_e32 v150, v146
	global_load_dwordx4 v[152:155], v151, s[24:25]
	v_add_u32_e32 v212, 0x1000, v151
	global_load_dwordx4 v[172:175], v212, s[24:25]
	v_add_u32_e32 v213, 0x10000, v151
	global_load_dwordx4 v[176:179], v213, s[24:25]
	v_add_u32_e32 v218, 0x11000, v151
	global_load_dwordx4 v[180:183], v218, s[24:25]
	v_add_u32_e32 v219, 0x20000, v151
	global_load_dwordx4 v[184:187], v219, s[24:25]
	v_add_u32_e32 v212, 0x21000, v151
	global_load_dwordx4 v[188:191], v212, s[24:25]
	v_add_u32_e32 v213, 0x30000, v151
	global_load_dwordx4 v[192:195], v213, s[24:25]
	v_add_u32_e32 v218, 0x31000, v151
	global_load_dwordx4 v[196:199], v218, s[24:25]
	v_add_u32_e32 v219, 0x80000, v151
	global_load_dwordx4 v[200:203], v219, s[24:25]
	v_add_u32_e32 v212, 0x81000, v151
	global_load_dwordx4 v[204:207], v212, s[24:25]
	v_add_u32_e32 v213, 0x90000, v151
	global_load_dwordx4 v[208:211], v213, s[24:25]
	v_add_u32_e32 v218, 0x91000, v151
	global_load_dwordx4 v[220:223], v218, s[24:25]
	v_add_u32_e32 v219, 0xa0000, v151
	global_load_dwordx4 v[224:227], v219, s[24:25]
	v_add_u32_e32 v212, 0xa1000, v151
	global_load_dwordx4 v[228:231], v212, s[24:25]
	v_add_u32_e32 v213, 0xb0000, v151
	global_load_dwordx4 v[232:235], v213, s[24:25]
	v_add_u32_e32 v218, 0xb1000, v151
	global_load_dwordx4 v[236:239], v218, s[24:25]
	v_cndmask_b32_e64 v158, v125, v117, s[6:7]
	v_mov_b32_e32 v161, 0
	v_cndmask_b32_e64 v167, v120, v112, s[6:7]
	v_mov_b32_e32 v168, 0
	v_cndmask_b32_e64 v156, v127, v119, s[6:7]
	v_mov_b32_e32 v163, 0
	v_cndmask_b32_e64 v166, v121, v113, s[6:7]
	v_mov_b32_e32 v169, 0
	v_mov_b32_dpp v161, v158 quad_perm:[1,0,3,2] row_mask:0xf bank_mask:0xf
	v_mov_b32_dpp v168, v167 quad_perm:[1,0,3,2] row_mask:0xf bank_mask:0xf
	v_mov_b32_dpp v163, v156 quad_perm:[1,0,3,2] row_mask:0xf bank_mask:0xf
	v_mov_b32_dpp v169, v166 quad_perm:[1,0,3,2] row_mask:0xf bank_mask:0xf
	v_cndmask_b32_e64 v125, v161, v125, s[6:7]
	v_cndmask_b32_e64 v120, v168, v120, s[6:7]
	v_cndmask_b32_e64 v127, v163, v127, s[6:7]
	v_cndmask_b32_e64 v121, v169, v121, s[6:7]
	v_mul_f32_e32 v125, 0xbfb8aa3b, v125
	v_mul_f32_e32 v120, 0xbfb8aa3b, v120
	v_mul_f32_e32 v127, 0xbfb8aa3b, v127
	v_mul_f32_e32 v121, 0xbfb8aa3b, v121
	v_exp_f32_e32 v125, v125
	v_exp_f32_e32 v120, v120
	v_cndmask_b32_e64 v165, v122, v114, s[6:7]
	v_mov_b32_e32 v170, 0
	v_exp_f32_e32 v127, v127
	v_exp_f32_e32 v121, v121
	v_cndmask_b32_e64 v159, v124, v116, s[6:7]
	v_mov_b32_e32 v160, 0
	v_cndmask_b32_e64 v164, v123, v115, s[6:7]
	v_mov_b32_e32 v171, 0
	v_mov_b32_dpp v170, v165 quad_perm:[1,0,3,2] row_mask:0xf bank_mask:0xf
	v_cndmask_b32_e64 v157, v126, v118, s[6:7]
	v_mov_b32_e32 v162, 0
	v_mov_b32_dpp v160, v159 quad_perm:[1,0,3,2] row_mask:0xf bank_mask:0xf
	v_mov_b32_dpp v171, v164 quad_perm:[1,0,3,2] row_mask:0xf bank_mask:0xf
	v_cndmask_b32_e64 v122, v170, v122, s[6:7]
	v_mov_b32_dpp v162, v157 quad_perm:[1,0,3,2] row_mask:0xf bank_mask:0xf
	v_cndmask_b32_e64 v124, v160, v124, s[6:7]
	v_cndmask_b32_e64 v123, v171, v123, s[6:7]
	v_mul_f32_e32 v122, 0xbfb8aa3b, v122
	v_add_f32_e32 v125, 1.0, v125
	v_add_f32_e32 v120, 1.0, v120
	v_cndmask_b32_e64 v126, v162, v126, s[6:7]
	v_mul_f32_e32 v124, 0xbfb8aa3b, v124
	v_mul_f32_e32 v123, 0xbfb8aa3b, v123
	v_exp_f32_e32 v122, v122
	v_add_f32_e32 v127, 1.0, v127
	v_add_f32_e32 v121, 1.0, v121
	v_rcp_f32_e32 v125, v125
	v_rcp_f32_e32 v120, v120
	v_mul_f32_e32 v126, 0xbfb8aa3b, v126
	v_exp_f32_e32 v124, v124
	v_exp_f32_e32 v123, v123
	v_rcp_f32_e32 v127, v127
	v_rcp_f32_e32 v121, v121
	v_exp_f32_e32 v126, v126
	v_add_f32_e32 v124, 1.0, v124
	s_lshl_b64 s[26:27], s[26:27], 21
	v_rcp_f32_e32 v124, v124
	v_add_f32_e32 v126, 1.0, v126
	s_add_u32 s17, s59, s26
	v_rcp_f32_e32 v126, v126
	s_addc_u32 s19, s60, s27
	s_add_u32 s26, s17, s54
	s_addc_u32 s27, s19, s55
	v_cndmask_b32_e64 v115, v115, v171, s[6:7]
	v_cndmask_b32_e64 v119, v119, v163, s[6:7]
	v_cndmask_b32_e64 v118, v118, v162, s[6:7]
	v_cndmask_b32_e64 v117, v117, v161, s[6:7]
	v_cndmask_b32_e64 v116, v116, v160, s[6:7]
	v_cndmask_b32_e64 v114, v114, v170, s[6:7]
	v_cndmask_b32_e64 v113, v113, v169, s[6:7]
	v_cndmask_b32_e64 v112, v112, v168, s[6:7]
	v_mul_f32_e32 v115, 0xbfb8aa3b, v115
	v_mul_f32_e32 v116, 0xbfb8aa3b, v116
	v_mul_f32_e32 v117, 0xbfb8aa3b, v117
	v_mul_f32_e32 v118, 0xbfb8aa3b, v118
	v_mul_f32_e32 v119, 0xbfb8aa3b, v119
	v_mul_f32_e32 v112, 0xbfb8aa3b, v112
	s_waitcnt vmcnt(15)
	v_lshlrev_b32_e32 v156, 16, v152
	v_and_b32_e32 v152, 0xffff0000, v152
	v_lshlrev_b32_e32 v158, 16, v154
	v_lshlrev_b32_e32 v157, 16, v153
	v_and_b32_e32 v153, 0xffff0000, v153
	v_and_b32_e32 v154, 0xffff0000, v154
	v_mul_f32_e32 v125, v125, v152
	v_mul_f32_e32 v152, v120, v158
	v_add_f32_e32 v120, 1.0, v122
	v_mul_f32_e32 v127, v127, v153
	v_mul_f32_e32 v153, v121, v154
	v_rcp_f32_e32 v120, v120
	v_add_f32_e32 v121, 1.0, v123
	v_rcp_f32_e32 v121, v121
	v_lshlrev_b32_e32 v122, 16, v155
	v_mul_f32_e32 v123, v120, v122
	v_and_b32_e32 v120, 0xffff0000, v155
	v_mul_f32_e32 v124, v124, v156
	v_mul_f32_e32 v154, v121, v120
	v_cvt_pk_bf16_f32 v120, v124, v125
	v_mul_f32_e32 v126, v126, v157
	v_cvt_pk_bf16_f32 v121, v126, v127
	v_cvt_pk_bf16_f32 v122, v152, v153
	v_cvt_pk_bf16_f32 v123, v123, v154
	global_store_dwordx4 v150, v[120:123], s[26:27]
	v_mul_f32_e32 v113, 0xbfb8aa3b, v113
	v_mul_f32_e32 v114, 0xbfb8aa3b, v114
	v_add_u32_e32 v120, 0x1000, v151
	s_waitcnt vmcnt(15)
;     __device__ __forceinline__ void operator()(const f32x4 (&acc)[2][2][4][2], const Unit& u, int wr, int wc, int fr, int fq, const EpiCtx& X) const {
;     ...
;         EPI_PIECES({ const unsigned goff = glo + (unsigned)(rl * W_SSM) * 2u, coff = clo + (unsigned)(rl * DM) * 2u;
;             GLU_ONE(p1a, p1b, goff, coff); GLU_ONE(p2a, p2b, goff + W_SSM * 2, coff + DM * 2); })
	s_nop 1
	v_mov_b32_e32 v120, v172
	v_mov_b32_e32 v121, v173
	v_mov_b32_e32 v122, v174
	v_mov_b32_e32 v123, v175
	v_exp_f32_e32 v115, v115
	v_exp_f32_e32 v116, v116
	v_exp_f32_e32 v117, v117
	v_exp_f32_e32 v118, v118
	v_exp_f32_e32 v119, v119
	v_exp_f32_e32 v112, v112
	v_exp_f32_e32 v113, v113
	v_exp_f32_e32 v114, v114
	v_add_f32_e32 v115, 1.0, v115
	v_add_f32_e32 v116, 1.0, v116
	v_add_f32_e32 v117, 1.0, v117
	v_add_f32_e32 v118, 1.0, v118
	v_add_f32_e32 v119, 1.0, v119
	v_add_f32_e32 v112, 1.0, v112
	v_add_f32_e32 v113, 1.0, v113
	v_add_f32_e32 v114, 1.0, v114
	v_rcp_f32_e32 v115, v115
	v_rcp_f32_e32 v116, v116
	v_rcp_f32_e32 v117, v117
	v_rcp_f32_e32 v118, v118
	v_rcp_f32_e32 v119, v119
	v_rcp_f32_e32 v112, v112
	v_rcp_f32_e32 v113, v113
	v_rcp_f32_e32 v114, v114
	v_add_u32_e32 v124, 0x2000, v150
	v_add_u32_e32 v125, 0x10000, v151
	v_mov_b32_e32 v155, 0
	v_mov_b32_e32 v154, 0
	s_andn2_b64 vcc, exec, s[8:9]
	s_mov_b64 s[8:9], -1
	v_lshlrev_b32_e32 v153, 16, v123
	v_and_b32_e32 v123, 0xffff0000, v123
	v_lshlrev_b32_e32 v126, 16, v120
	v_and_b32_e32 v120, 0xffff0000, v120
	v_lshlrev_b32_e32 v127, 16, v121
	v_and_b32_e32 v121, 0xffff0000, v121
	v_lshlrev_b32_e32 v152, 16, v122
	v_and_b32_e32 v122, 0xffff0000, v122
	v_mul_f32_e32 v115, v115, v123
	v_mul_f32_e32 v116, v116, v126
	v_mul_f32_e32 v117, v117, v120
	v_mul_f32_e32 v118, v118, v127
	v_mul_f32_e32 v119, v119, v121
	v_mul_f32_e32 v120, v112, v152
	v_mul_f32_e32 v121, v113, v122
	v_mul_f32_e32 v122, v114, v153
	v_cvt_pk_bf16_f32 v112, v116, v117
	v_cvt_pk_bf16_f32 v113, v118, v119
	v_cvt_pk_bf16_f32 v114, v120, v121
	v_cvt_pk_bf16_f32 v115, v122, v115
	global_store_dwordx4 v124, v[112:115], s[26:27]
	s_waitcnt vmcnt(15)
	s_nop 1
	v_mov_b32_e32 v112, v176
	v_mov_b32_e32 v113, v177
	v_mov_b32_e32 v114, v178
	v_mov_b32_e32 v115, v179
	v_cndmask_b32_e64 v124, v107, v99, s[6:7]
	v_cndmask_b32_e64 v116, v111, v103, s[6:7]
	v_cndmask_b32_e64 v117, v110, v102, s[6:7]
	v_cndmask_b32_e64 v118, v109, v101, s[6:7]
	v_cndmask_b32_e64 v119, v108, v100, s[6:7]
	v_mov_b32_e32 v120, 0
	v_mov_b32_e32 v121, 0
	v_mov_b32_e32 v122, 0
	v_mov_b32_e32 v123, 0
	v_cndmask_b32_e64 v125, v106, v98, s[6:7]
	v_cndmask_b32_e64 v126, v105, v97, s[6:7]
	v_cndmask_b32_e64 v127, v104, v96, s[6:7]
	v_mov_b32_e32 v152, 0
	v_mov_b32_e32 v153, 0
	v_mov_b32_dpp v155, v124 quad_perm:[1,0,3,2] row_mask:0xf bank_mask:0xf
	v_mov_b32_dpp v120, v119 quad_perm:[1,0,3,2] row_mask:0xf bank_mask:0xf
	v_mov_b32_dpp v121, v118 quad_perm:[1,0,3,2] row_mask:0xf bank_mask:0xf
	v_mov_b32_dpp v122, v117 quad_perm:[1,0,3,2] row_mask:0xf bank_mask:0xf
	v_mov_b32_dpp v123, v116 quad_perm:[1,0,3,2] row_mask:0xf bank_mask:0xf
	v_mov_b32_dpp v152, v127 quad_perm:[1,0,3,2] row_mask:0xf bank_mask:0xf
	v_mov_b32_dpp v153, v126 quad_perm:[1,0,3,2] row_mask:0xf bank_mask:0xf
	v_mov_b32_dpp v154, v125 quad_perm:[1,0,3,2] row_mask:0xf bank_mask:0xf
	v_cndmask_b32_e64 v107, v155, v107, s[6:7]
	v_cndmask_b32_e64 v111, v123, v111, s[6:7]
	v_cndmask_b32_e64 v110, v122, v110, s[6:7]
	v_cndmask_b32_e64 v109, v121, v109, s[6:7]
	v_cndmask_b32_e64 v108, v120, v108, s[6:7]
	v_cndmask_b32_e64 v106, v154, v106, s[6:7]
	v_cndmask_b32_e64 v105, v153, v105, s[6:7]
	v_cndmask_b32_e64 v104, v152, v104, s[6:7]
	v_mul_f32_e32 v107, 0xbfb8aa3b, v107
	v_mul_f32_e32 v108, 0xbfb8aa3b, v108
	v_mul_f32_e32 v109, 0xbfb8aa3b, v109
	v_mul_f32_e32 v110, 0xbfb8aa3b, v110
	v_mul_f32_e32 v111, 0xbfb8aa3b, v111
	v_mul_f32_e32 v104, 0xbfb8aa3b, v104
	v_mul_f32_e32 v105, 0xbfb8aa3b, v105
	v_mul_f32_e32 v106, 0xbfb8aa3b, v106
	v_exp_f32_e32 v107, v107
	v_exp_f32_e32 v108, v108
	v_exp_f32_e32 v109, v109
	v_exp_f32_e32 v110, v110
	v_exp_f32_e32 v111, v111
	v_exp_f32_e32 v104, v104
	v_exp_f32_e32 v105, v105
	v_exp_f32_e32 v106, v106
	v_add_f32_e32 v107, 1.0, v107
	v_add_f32_e32 v108, 1.0, v108
	v_add_f32_e32 v109, 1.0, v109
	v_add_f32_e32 v110, 1.0, v110
	v_add_f32_e32 v111, 1.0, v111
	v_add_f32_e32 v104, 1.0, v104
	v_add_f32_e32 v105, 1.0, v105
	v_add_f32_e32 v106, 1.0, v106
	v_rcp_f32_e32 v107, v107
	v_rcp_f32_e32 v108, v108
	v_rcp_f32_e32 v109, v109
	v_rcp_f32_e32 v110, v110
	v_rcp_f32_e32 v111, v111
	v_rcp_f32_e32 v104, v104
	v_rcp_f32_e32 v105, v105
	v_rcp_f32_e32 v106, v106
	v_add_u32_e32 v116, 0x20000, v150
	v_add_u32_e32 v117, 0x11000, v151
	v_cndmask_b32_e64 v99, v99, v155, s[6:7]
	v_cndmask_b32_e64 v103, v103, v123, s[6:7]
	v_cndmask_b32_e64 v102, v102, v122, s[6:7]
	v_cndmask_b32_e64 v101, v101, v121, s[6:7]
	v_cndmask_b32_e64 v100, v100, v120, s[6:7]
	v_cndmask_b32_e64 v98, v98, v154, s[6:7]
	v_cndmask_b32_e64 v97, v97, v153, s[6:7]
	v_cndmask_b32_e64 v96, v96, v152, s[6:7]
	v_mul_f32_e32 v99, 0xbfb8aa3b, v99
	v_mul_f32_e32 v100, 0xbfb8aa3b, v100
	v_mul_f32_e32 v101, 0xbfb8aa3b, v101
	v_mul_f32_e32 v102, 0xbfb8aa3b, v102
	v_mul_f32_e32 v103, 0xbfb8aa3b, v103
	v_mul_f32_e32 v96, 0xbfb8aa3b, v96
	v_mul_f32_e32 v97, 0xbfb8aa3b, v97
	v_lshlrev_b32_e32 v125, 16, v115
	v_and_b32_e32 v115, 0xffff0000, v115
	v_lshlrev_b32_e32 v118, 16, v112
	v_and_b32_e32 v112, 0xffff0000, v112
	v_lshlrev_b32_e32 v119, 16, v113
	v_and_b32_e32 v113, 0xffff0000, v113
	v_lshlrev_b32_e32 v124, 16, v114
	v_and_b32_e32 v114, 0xffff0000, v114
	v_mul_f32_e32 v107, v107, v115
	v_mul_f32_e32 v108, v108, v118
	v_mul_f32_e32 v109, v109, v112
	v_mul_f32_e32 v110, v110, v119
	v_mul_f32_e32 v111, v111, v113
	v_mul_f32_e32 v112, v104, v124
	v_mul_f32_e32 v113, v105, v114
	v_mul_f32_e32 v114, v106, v125
	v_cvt_pk_bf16_f32 v104, v108, v109
	v_cvt_pk_bf16_f32 v105, v110, v111
	v_cvt_pk_bf16_f32 v106, v112, v113
	v_cvt_pk_bf16_f32 v107, v114, v107
	global_store_dwordx4 v116, v[104:107], s[26:27]
	s_waitcnt vmcnt(15)
;     __device__ __forceinline__ void operator()(const f32x4 (&acc)[2][2][4][2], const Unit& u, int wr, int wc, int fr, int fq, const EpiCtx& X) const {
;     ...
;         EPI_PIECES({ const unsigned goff = glo + (unsigned)(rl * W_SSM) * 2u, coff = clo + (unsigned)(rl * DM) * 2u;
;             GLU_ONE(p1a, p1b, goff, coff); GLU_ONE(p2a, p2b, goff + W_SSM * 2, coff + DM * 2); })
	s_nop 1
	v_mov_b32_e32 v104, v180
	v_mov_b32_e32 v105, v181
	v_mov_b32_e32 v106, v182
	v_mov_b32_e32 v107, v183
	v_mul_f32_e32 v98, 0xbfb8aa3b, v98
	v_exp_f32_e32 v99, v99
	v_exp_f32_e32 v100, v100
	v_exp_f32_e32 v101, v101
	v_exp_f32_e32 v102, v102
	v_exp_f32_e32 v103, v103
	v_exp_f32_e32 v96, v96
	v_exp_f32_e32 v97, v97
	v_exp_f32_e32 v98, v98
	v_add_f32_e32 v99, 1.0, v99
	v_add_f32_e32 v100, 1.0, v100
	v_add_f32_e32 v101, 1.0, v101
	v_add_f32_e32 v102, 1.0, v102
	v_add_f32_e32 v103, 1.0, v103
	v_add_f32_e32 v96, 1.0, v96
	v_add_f32_e32 v97, 1.0, v97
	v_add_f32_e32 v98, 1.0, v98
	v_rcp_f32_e32 v99, v99
	v_rcp_f32_e32 v100, v100
	v_rcp_f32_e32 v101, v101
	v_rcp_f32_e32 v102, v102
	v_rcp_f32_e32 v103, v103
	v_rcp_f32_e32 v96, v96
	v_rcp_f32_e32 v97, v97
	v_rcp_f32_e32 v98, v98
	v_add_u32_e32 v108, 0x22000, v150
	v_add_u32_e32 v109, 0x20000, v151
	v_mov_b32_e32 v115, 0
	v_mov_b32_e32 v114, 0
	v_lshlrev_b32_e32 v113, 16, v107
	v_and_b32_e32 v107, 0xffff0000, v107
	v_lshlrev_b32_e32 v110, 16, v104
	v_and_b32_e32 v104, 0xffff0000, v104
	v_lshlrev_b32_e32 v111, 16, v105
	v_and_b32_e32 v105, 0xffff0000, v105
	v_lshlrev_b32_e32 v112, 16, v106
	v_and_b32_e32 v106, 0xffff0000, v106
	v_mul_f32_e32 v99, v99, v107
	v_mul_f32_e32 v100, v100, v110
	v_mul_f32_e32 v101, v101, v104
	v_mul_f32_e32 v102, v102, v111
	v_mul_f32_e32 v103, v103, v105
	v_mul_f32_e32 v104, v96, v112
	v_mul_f32_e32 v105, v97, v106
	v_mul_f32_e32 v106, v98, v113
	v_cvt_pk_bf16_f32 v96, v100, v101
	v_cvt_pk_bf16_f32 v97, v102, v103
	v_cvt_pk_bf16_f32 v98, v104, v105
	v_cvt_pk_bf16_f32 v99, v106, v99
	global_store_dwordx4 v108, v[96:99], s[26:27]
	s_waitcnt vmcnt(15)
	s_nop 1
	v_mov_b32_e32 v96, v184
	v_mov_b32_e32 v97, v185
	v_mov_b32_e32 v98, v186
	v_mov_b32_e32 v99, v187
	v_cndmask_b32_e64 v108, v91, v83, s[6:7]
	v_cndmask_b32_e64 v100, v95, v87, s[6:7]
	v_cndmask_b32_e64 v101, v94, v86, s[6:7]
	v_cndmask_b32_e64 v102, v93, v85, s[6:7]
	v_cndmask_b32_e64 v103, v92, v84, s[6:7]
	v_mov_b32_e32 v104, 0
	v_mov_b32_e32 v105, 0
	v_mov_b32_e32 v106, 0
	v_mov_b32_e32 v107, 0
	v_cndmask_b32_e64 v109, v90, v82, s[6:7]
	v_cndmask_b32_e64 v110, v89, v81, s[6:7]
	v_cndmask_b32_e64 v111, v88, v80, s[6:7]
	v_mov_b32_e32 v112, 0
	v_mov_b32_e32 v113, 0
	v_mov_b32_dpp v115, v108 quad_perm:[1,0,3,2] row_mask:0xf bank_mask:0xf
	v_mov_b32_dpp v104, v103 quad_perm:[1,0,3,2] row_mask:0xf bank_mask:0xf
	v_mov_b32_dpp v105, v102 quad_perm:[1,0,3,2] row_mask:0xf bank_mask:0xf
	v_mov_b32_dpp v106, v101 quad_perm:[1,0,3,2] row_mask:0xf bank_mask:0xf
	v_mov_b32_dpp v107, v100 quad_perm:[1,0,3,2] row_mask:0xf bank_mask:0xf
	v_mov_b32_dpp v112, v111 quad_perm:[1,0,3,2] row_mask:0xf bank_mask:0xf
	v_mov_b32_dpp v113, v110 quad_perm:[1,0,3,2] row_mask:0xf bank_mask:0xf
	v_mov_b32_dpp v114, v109 quad_perm:[1,0,3,2] row_mask:0xf bank_mask:0xf
	v_cndmask_b32_e64 v91, v115, v91, s[6:7]
	v_cndmask_b32_e64 v95, v107, v95, s[6:7]
	v_cndmask_b32_e64 v94, v106, v94, s[6:7]
	v_cndmask_b32_e64 v93, v105, v93, s[6:7]
	v_cndmask_b32_e64 v92, v104, v92, s[6:7]
	v_cndmask_b32_e64 v90, v114, v90, s[6:7]
	v_cndmask_b32_e64 v89, v113, v89, s[6:7]
	v_cndmask_b32_e64 v88, v112, v88, s[6:7]
	v_mul_f32_e32 v91, 0xbfb8aa3b, v91
	v_mul_f32_e32 v92, 0xbfb8aa3b, v92
	v_mul_f32_e32 v93, 0xbfb8aa3b, v93
	v_mul_f32_e32 v94, 0xbfb8aa3b, v94
	v_mul_f32_e32 v95, 0xbfb8aa3b, v95
	v_mul_f32_e32 v88, 0xbfb8aa3b, v88
	v_mul_f32_e32 v89, 0xbfb8aa3b, v89
	v_mul_f32_e32 v90, 0xbfb8aa3b, v90
	v_exp_f32_e32 v91, v91
	v_exp_f32_e32 v92, v92
	v_exp_f32_e32 v93, v93
	v_exp_f32_e32 v94, v94
	v_exp_f32_e32 v95, v95
	v_exp_f32_e32 v88, v88
	v_exp_f32_e32 v89, v89
	v_exp_f32_e32 v90, v90
	v_add_f32_e32 v91, 1.0, v91
	v_add_f32_e32 v92, 1.0, v92
	v_add_f32_e32 v93, 1.0, v93
	v_add_f32_e32 v94, 1.0, v94
	v_add_f32_e32 v95, 1.0, v95
	v_add_f32_e32 v88, 1.0, v88
	v_add_f32_e32 v89, 1.0, v89
	v_add_f32_e32 v90, 1.0, v90
	v_rcp_f32_e32 v91, v91
	v_rcp_f32_e32 v92, v92
	v_rcp_f32_e32 v93, v93
	v_rcp_f32_e32 v94, v94
	v_rcp_f32_e32 v95, v95
	v_rcp_f32_e32 v88, v88
	v_rcp_f32_e32 v89, v89
	v_rcp_f32_e32 v90, v90
	v_add_u32_e32 v100, 0x40000, v150
	v_add_u32_e32 v101, 0x21000, v151
	v_cndmask_b32_e64 v83, v83, v115, s[6:7]
	v_cndmask_b32_e64 v87, v87, v107, s[6:7]
	v_cndmask_b32_e64 v86, v86, v106, s[6:7]
	v_cndmask_b32_e64 v85, v85, v105, s[6:7]
	v_cndmask_b32_e64 v84, v84, v104, s[6:7]
	v_cndmask_b32_e64 v82, v82, v114, s[6:7]
	v_cndmask_b32_e64 v81, v81, v113, s[6:7]
	v_cndmask_b32_e64 v80, v80, v112, s[6:7]
	v_mul_f32_e32 v83, 0xbfb8aa3b, v83
	v_mul_f32_e32 v84, 0xbfb8aa3b, v84
	v_mul_f32_e32 v85, 0xbfb8aa3b, v85
	v_mul_f32_e32 v86, 0xbfb8aa3b, v86
	v_mul_f32_e32 v87, 0xbfb8aa3b, v87
	v_mul_f32_e32 v80, 0xbfb8aa3b, v80
	v_mul_f32_e32 v81, 0xbfb8aa3b, v81
	v_lshlrev_b32_e32 v109, 16, v99
	v_and_b32_e32 v99, 0xffff0000, v99
	v_lshlrev_b32_e32 v102, 16, v96
	v_and_b32_e32 v96, 0xffff0000, v96
	v_lshlrev_b32_e32 v103, 16, v97
	v_and_b32_e32 v97, 0xffff0000, v97
	v_lshlrev_b32_e32 v108, 16, v98
	v_and_b32_e32 v98, 0xffff0000, v98
	v_mul_f32_e32 v91, v91, v99
	v_mul_f32_e32 v92, v92, v102
	v_mul_f32_e32 v93, v93, v96
	v_mul_f32_e32 v94, v94, v103
	v_mul_f32_e32 v95, v95, v97
	v_mul_f32_e32 v96, v88, v108
	v_mul_f32_e32 v97, v89, v98
	v_mul_f32_e32 v98, v90, v109
	v_cvt_pk_bf16_f32 v88, v92, v93
	v_cvt_pk_bf16_f32 v89, v94, v95
	v_cvt_pk_bf16_f32 v90, v96, v97
	v_cvt_pk_bf16_f32 v91, v98, v91
	global_store_dwordx4 v100, v[88:91], s[26:27]
	s_waitcnt vmcnt(15)
;     __device__ __forceinline__ void operator()(const f32x4 (&acc)[2][2][4][2], const Unit& u, int wr, int wc, int fr, int fq, const EpiCtx& X) const {
;     ...
;         EPI_PIECES({ const unsigned goff = glo + (unsigned)(rl * W_SSM) * 2u, coff = clo + (unsigned)(rl * DM) * 2u;
;             GLU_ONE(p1a, p1b, goff, coff); GLU_ONE(p2a, p2b, goff + W_SSM * 2, coff + DM * 2); })
	s_nop 1
	v_mov_b32_e32 v88, v188
	v_mov_b32_e32 v89, v189
	v_mov_b32_e32 v90, v190
	v_mov_b32_e32 v91, v191
	v_mul_f32_e32 v82, 0xbfb8aa3b, v82
	v_exp_f32_e32 v83, v83
	v_exp_f32_e32 v84, v84
	v_exp_f32_e32 v85, v85
	v_exp_f32_e32 v86, v86
	v_exp_f32_e32 v87, v87
	v_exp_f32_e32 v80, v80
	v_exp_f32_e32 v81, v81
	v_exp_f32_e32 v82, v82
	v_add_f32_e32 v83, 1.0, v83
	v_add_f32_e32 v84, 1.0, v84
	v_add_f32_e32 v85, 1.0, v85
	v_add_f32_e32 v86, 1.0, v86
	v_add_f32_e32 v87, 1.0, v87
	v_add_f32_e32 v80, 1.0, v80
	v_add_f32_e32 v81, 1.0, v81
	v_add_f32_e32 v82, 1.0, v82
	v_rcp_f32_e32 v83, v83
	v_rcp_f32_e32 v84, v84
	v_rcp_f32_e32 v85, v85
	v_rcp_f32_e32 v86, v86
	v_rcp_f32_e32 v87, v87
	v_rcp_f32_e32 v80, v80
	v_rcp_f32_e32 v81, v81
	v_rcp_f32_e32 v82, v82
	v_add_u32_e32 v92, 0x42000, v150
	v_add_u32_e32 v93, 0x30000, v151
	v_mov_b32_e32 v99, 0
	v_mov_b32_e32 v98, 0
	v_lshlrev_b32_e32 v97, 16, v91
	v_and_b32_e32 v91, 0xffff0000, v91
	v_lshlrev_b32_e32 v94, 16, v88
	v_and_b32_e32 v88, 0xffff0000, v88
	v_lshlrev_b32_e32 v95, 16, v89
	v_and_b32_e32 v89, 0xffff0000, v89
	v_lshlrev_b32_e32 v96, 16, v90
	v_and_b32_e32 v90, 0xffff0000, v90
	v_mul_f32_e32 v83, v83, v91
	v_mul_f32_e32 v84, v84, v94
	v_mul_f32_e32 v85, v85, v88
	v_mul_f32_e32 v86, v86, v95
	v_mul_f32_e32 v87, v87, v89
	v_mul_f32_e32 v88, v80, v96
	v_mul_f32_e32 v89, v81, v90
	v_mul_f32_e32 v90, v82, v97
	v_cvt_pk_bf16_f32 v80, v84, v85
	v_cvt_pk_bf16_f32 v81, v86, v87
	v_cvt_pk_bf16_f32 v82, v88, v89
	v_cvt_pk_bf16_f32 v83, v90, v83
	global_store_dwordx4 v92, v[80:83], s[26:27]
	s_waitcnt vmcnt(15)
	s_nop 1
	v_mov_b32_e32 v80, v192
	v_mov_b32_e32 v81, v193
	v_mov_b32_e32 v82, v194
	v_mov_b32_e32 v83, v195
	v_cndmask_b32_e64 v92, v75, v67, s[6:7]
	v_cndmask_b32_e64 v84, v79, v71, s[6:7]
	v_cndmask_b32_e64 v85, v78, v70, s[6:7]
	v_cndmask_b32_e64 v86, v77, v69, s[6:7]
	v_cndmask_b32_e64 v87, v76, v68, s[6:7]
	v_mov_b32_e32 v88, 0
	v_mov_b32_e32 v89, 0
	v_mov_b32_e32 v90, 0
	v_mov_b32_e32 v91, 0
	v_cndmask_b32_e64 v93, v74, v66, s[6:7]
	v_cndmask_b32_e64 v94, v73, v65, s[6:7]
	v_cndmask_b32_e64 v95, v72, v64, s[6:7]
	v_mov_b32_e32 v96, 0
	v_mov_b32_e32 v97, 0
	v_mov_b32_dpp v99, v92 quad_perm:[1,0,3,2] row_mask:0xf bank_mask:0xf
	v_mov_b32_dpp v88, v87 quad_perm:[1,0,3,2] row_mask:0xf bank_mask:0xf
	v_mov_b32_dpp v89, v86 quad_perm:[1,0,3,2] row_mask:0xf bank_mask:0xf
	v_mov_b32_dpp v90, v85 quad_perm:[1,0,3,2] row_mask:0xf bank_mask:0xf
	v_mov_b32_dpp v91, v84 quad_perm:[1,0,3,2] row_mask:0xf bank_mask:0xf
	v_mov_b32_dpp v96, v95 quad_perm:[1,0,3,2] row_mask:0xf bank_mask:0xf
	v_mov_b32_dpp v97, v94 quad_perm:[1,0,3,2] row_mask:0xf bank_mask:0xf
	v_mov_b32_dpp v98, v93 quad_perm:[1,0,3,2] row_mask:0xf bank_mask:0xf
	v_cndmask_b32_e64 v75, v99, v75, s[6:7]
	v_cndmask_b32_e64 v79, v91, v79, s[6:7]
	v_cndmask_b32_e64 v78, v90, v78, s[6:7]
	v_cndmask_b32_e64 v77, v89, v77, s[6:7]
	v_cndmask_b32_e64 v76, v88, v76, s[6:7]
	v_cndmask_b32_e64 v74, v98, v74, s[6:7]
	v_cndmask_b32_e64 v73, v97, v73, s[6:7]
	v_cndmask_b32_e64 v72, v96, v72, s[6:7]
	v_mul_f32_e32 v75, 0xbfb8aa3b, v75
	v_mul_f32_e32 v76, 0xbfb8aa3b, v76
	v_mul_f32_e32 v77, 0xbfb8aa3b, v77
	v_mul_f32_e32 v78, 0xbfb8aa3b, v78
	v_mul_f32_e32 v79, 0xbfb8aa3b, v79
	v_mul_f32_e32 v72, 0xbfb8aa3b, v72
	v_mul_f32_e32 v73, 0xbfb8aa3b, v73
	v_mul_f32_e32 v74, 0xbfb8aa3b, v74
	v_exp_f32_e32 v75, v75
	v_exp_f32_e32 v76, v76
	v_exp_f32_e32 v77, v77
	v_exp_f32_e32 v78, v78
	v_exp_f32_e32 v79, v79
	v_exp_f32_e32 v72, v72
	v_exp_f32_e32 v73, v73
	v_exp_f32_e32 v74, v74
	v_add_f32_e32 v75, 1.0, v75
	v_add_f32_e32 v76, 1.0, v76
	v_add_f32_e32 v77, 1.0, v77
	v_add_f32_e32 v78, 1.0, v78
	v_add_f32_e32 v79, 1.0, v79
	v_add_f32_e32 v72, 1.0, v72
	v_add_f32_e32 v73, 1.0, v73
	v_add_f32_e32 v74, 1.0, v74
	v_rcp_f32_e32 v75, v75
	v_rcp_f32_e32 v76, v76
	v_rcp_f32_e32 v77, v77
	v_rcp_f32_e32 v78, v78
	v_rcp_f32_e32 v79, v79
	v_rcp_f32_e32 v72, v72
	v_rcp_f32_e32 v73, v73
	v_rcp_f32_e32 v74, v74
	v_add_u32_e32 v84, 0x60000, v150
	v_add_u32_e32 v85, 0x31000, v151
	v_cndmask_b32_e64 v67, v67, v99, s[6:7]
	v_cndmask_b32_e64 v71, v71, v91, s[6:7]
	v_cndmask_b32_e64 v70, v70, v90, s[6:7]
	v_cndmask_b32_e64 v69, v69, v89, s[6:7]
	v_cndmask_b32_e64 v68, v68, v88, s[6:7]
	v_cndmask_b32_e64 v66, v66, v98, s[6:7]
	v_cndmask_b32_e64 v65, v65, v97, s[6:7]
	v_cndmask_b32_e64 v64, v64, v96, s[6:7]
	v_mul_f32_e32 v67, 0xbfb8aa3b, v67
	v_mul_f32_e32 v68, 0xbfb8aa3b, v68
	v_mul_f32_e32 v69, 0xbfb8aa3b, v69
	v_mul_f32_e32 v70, 0xbfb8aa3b, v70
	v_mul_f32_e32 v71, 0xbfb8aa3b, v71
	v_mul_f32_e32 v64, 0xbfb8aa3b, v64
	v_mul_f32_e32 v65, 0xbfb8aa3b, v65
	v_lshlrev_b32_e32 v93, 16, v83
	v_and_b32_e32 v83, 0xffff0000, v83
	v_lshlrev_b32_e32 v86, 16, v80
	v_and_b32_e32 v80, 0xffff0000, v80
	v_lshlrev_b32_e32 v87, 16, v81
	v_and_b32_e32 v81, 0xffff0000, v81
	v_lshlrev_b32_e32 v92, 16, v82
	v_and_b32_e32 v82, 0xffff0000, v82
	v_mul_f32_e32 v75, v75, v83
	v_mul_f32_e32 v76, v76, v86
	v_mul_f32_e32 v77, v77, v80
	v_mul_f32_e32 v78, v78, v87
	v_mul_f32_e32 v79, v79, v81
	v_mul_f32_e32 v80, v72, v92
	v_mul_f32_e32 v81, v73, v82
	v_mul_f32_e32 v82, v74, v93
	v_cvt_pk_bf16_f32 v72, v76, v77
	v_cvt_pk_bf16_f32 v73, v78, v79
	v_cvt_pk_bf16_f32 v74, v80, v81
	v_cvt_pk_bf16_f32 v75, v82, v75
	global_store_dwordx4 v84, v[72:75], s[26:27]
	s_waitcnt vmcnt(15)
;     __device__ __forceinline__ void operator()(const f32x4 (&acc)[2][2][4][2], const Unit& u, int wr, int wc, int fr, int fq, const EpiCtx& X) const {
;     ...
;         EPI_PIECES({ const unsigned goff = glo + (unsigned)(rl * W_SSM) * 2u, coff = clo + (unsigned)(rl * DM) * 2u;
;             GLU_ONE(p1a, p1b, goff, coff); GLU_ONE(p2a, p2b, goff + W_SSM * 2, coff + DM * 2); })
	s_nop 1
	v_mov_b32_e32 v72, v196
	v_mov_b32_e32 v73, v197
	v_mov_b32_e32 v74, v198
	v_mov_b32_e32 v75, v199
	v_mul_f32_e32 v66, 0xbfb8aa3b, v66
	v_exp_f32_e32 v67, v67
	v_exp_f32_e32 v68, v68
	v_exp_f32_e32 v69, v69
	v_exp_f32_e32 v70, v70
	v_exp_f32_e32 v71, v71
	v_exp_f32_e32 v64, v64
	v_exp_f32_e32 v65, v65
	v_exp_f32_e32 v66, v66
	v_add_f32_e32 v67, 1.0, v67
	v_add_f32_e32 v68, 1.0, v68
	v_add_f32_e32 v69, 1.0, v69
	v_add_f32_e32 v70, 1.0, v70
	v_add_f32_e32 v71, 1.0, v71
	v_add_f32_e32 v64, 1.0, v64
	v_add_f32_e32 v65, 1.0, v65
	v_add_f32_e32 v66, 1.0, v66
	v_rcp_f32_e32 v67, v67
	v_rcp_f32_e32 v68, v68
	v_rcp_f32_e32 v69, v69
	v_rcp_f32_e32 v70, v70
	v_rcp_f32_e32 v71, v71
	v_rcp_f32_e32 v64, v64
	v_rcp_f32_e32 v65, v65
	v_rcp_f32_e32 v66, v66
	v_add_u32_e32 v76, 0x62000, v150
	v_add_u32_e32 v77, 0x80000, v151
	v_mov_b32_e32 v83, 0
	v_mov_b32_e32 v82, 0
	v_lshlrev_b32_e32 v81, 16, v75
	v_and_b32_e32 v75, 0xffff0000, v75
	v_lshlrev_b32_e32 v78, 16, v72
	v_and_b32_e32 v72, 0xffff0000, v72
	v_lshlrev_b32_e32 v79, 16, v73
	v_and_b32_e32 v73, 0xffff0000, v73
	v_lshlrev_b32_e32 v80, 16, v74
	v_and_b32_e32 v74, 0xffff0000, v74
	v_mul_f32_e32 v67, v67, v75
	v_mul_f32_e32 v68, v68, v78
	v_mul_f32_e32 v69, v69, v72
	v_mul_f32_e32 v70, v70, v79
	v_mul_f32_e32 v71, v71, v73
	v_mul_f32_e32 v72, v64, v80
	v_mul_f32_e32 v73, v65, v74
	v_mul_f32_e32 v74, v66, v81
	v_cvt_pk_bf16_f32 v64, v68, v69
	v_cvt_pk_bf16_f32 v65, v70, v71
	v_cvt_pk_bf16_f32 v66, v72, v73
	v_cvt_pk_bf16_f32 v67, v74, v67
	global_store_dwordx4 v76, v[64:67], s[26:27]
	s_waitcnt vmcnt(15)
	s_nop 1
	v_mov_b32_e32 v64, v200
	v_mov_b32_e32 v65, v201
	v_mov_b32_e32 v66, v202
	v_mov_b32_e32 v67, v203
	v_cndmask_b32_e64 v76, v59, v51, s[6:7]
	v_cndmask_b32_e64 v68, v63, v55, s[6:7]
	v_cndmask_b32_e64 v69, v62, v54, s[6:7]
	v_cndmask_b32_e64 v70, v61, v53, s[6:7]
	v_cndmask_b32_e64 v71, v60, v52, s[6:7]
	v_mov_b32_e32 v72, 0
	v_mov_b32_e32 v73, 0
	v_mov_b32_e32 v74, 0
	v_mov_b32_e32 v75, 0
	v_cndmask_b32_e64 v77, v58, v50, s[6:7]
	v_cndmask_b32_e64 v78, v57, v49, s[6:7]
	v_cndmask_b32_e64 v79, v56, v48, s[6:7]
	v_mov_b32_e32 v80, 0
	v_mov_b32_e32 v81, 0
	v_mov_b32_dpp v83, v76 quad_perm:[1,0,3,2] row_mask:0xf bank_mask:0xf
	v_mov_b32_dpp v72, v71 quad_perm:[1,0,3,2] row_mask:0xf bank_mask:0xf
	v_mov_b32_dpp v73, v70 quad_perm:[1,0,3,2] row_mask:0xf bank_mask:0xf
	v_mov_b32_dpp v74, v69 quad_perm:[1,0,3,2] row_mask:0xf bank_mask:0xf
	v_mov_b32_dpp v75, v68 quad_perm:[1,0,3,2] row_mask:0xf bank_mask:0xf
	v_mov_b32_dpp v80, v79 quad_perm:[1,0,3,2] row_mask:0xf bank_mask:0xf
	v_mov_b32_dpp v81, v78 quad_perm:[1,0,3,2] row_mask:0xf bank_mask:0xf
	v_mov_b32_dpp v82, v77 quad_perm:[1,0,3,2] row_mask:0xf bank_mask:0xf
	v_cndmask_b32_e64 v59, v83, v59, s[6:7]
	v_cndmask_b32_e64 v63, v75, v63, s[6:7]
	v_cndmask_b32_e64 v62, v74, v62, s[6:7]
	v_cndmask_b32_e64 v61, v73, v61, s[6:7]
	v_cndmask_b32_e64 v60, v72, v60, s[6:7]
	v_cndmask_b32_e64 v58, v82, v58, s[6:7]
	v_cndmask_b32_e64 v57, v81, v57, s[6:7]
	v_cndmask_b32_e64 v56, v80, v56, s[6:7]
	v_mul_f32_e32 v59, 0xbfb8aa3b, v59
	v_mul_f32_e32 v60, 0xbfb8aa3b, v60
	v_mul_f32_e32 v61, 0xbfb8aa3b, v61
	v_mul_f32_e32 v62, 0xbfb8aa3b, v62
	v_mul_f32_e32 v63, 0xbfb8aa3b, v63
	v_mul_f32_e32 v56, 0xbfb8aa3b, v56
	v_mul_f32_e32 v57, 0xbfb8aa3b, v57
	v_mul_f32_e32 v58, 0xbfb8aa3b, v58
	v_exp_f32_e32 v59, v59
	v_exp_f32_e32 v60, v60
	v_exp_f32_e32 v61, v61
	v_exp_f32_e32 v62, v62
	v_exp_f32_e32 v63, v63
	v_exp_f32_e32 v56, v56
	v_exp_f32_e32 v57, v57
	v_exp_f32_e32 v58, v58
	v_add_f32_e32 v59, 1.0, v59
	v_add_f32_e32 v60, 1.0, v60
	v_add_f32_e32 v61, 1.0, v61
	v_add_f32_e32 v62, 1.0, v62
	v_add_f32_e32 v63, 1.0, v63
	v_add_f32_e32 v56, 1.0, v56
	v_add_f32_e32 v57, 1.0, v57
	v_add_f32_e32 v58, 1.0, v58
	v_rcp_f32_e32 v59, v59
	v_rcp_f32_e32 v60, v60
	v_rcp_f32_e32 v61, v61
	v_rcp_f32_e32 v62, v62
	v_rcp_f32_e32 v63, v63
	v_rcp_f32_e32 v56, v56
	v_rcp_f32_e32 v57, v57
	v_rcp_f32_e32 v58, v58
	v_add_u32_e32 v68, 0x100000, v150
	v_add_u32_e32 v69, 0x81000, v151
	v_cndmask_b32_e64 v51, v51, v83, s[6:7]
	v_cndmask_b32_e64 v55, v55, v75, s[6:7]
	v_cndmask_b32_e64 v54, v54, v74, s[6:7]
	v_cndmask_b32_e64 v53, v53, v73, s[6:7]
	v_cndmask_b32_e64 v52, v52, v72, s[6:7]
	v_cndmask_b32_e64 v50, v50, v82, s[6:7]
	v_cndmask_b32_e64 v49, v49, v81, s[6:7]
	v_cndmask_b32_e64 v48, v48, v80, s[6:7]
	v_mul_f32_e32 v51, 0xbfb8aa3b, v51
	v_mul_f32_e32 v52, 0xbfb8aa3b, v52
	v_mul_f32_e32 v53, 0xbfb8aa3b, v53
	v_mul_f32_e32 v54, 0xbfb8aa3b, v54
	v_mul_f32_e32 v55, 0xbfb8aa3b, v55
	v_mul_f32_e32 v48, 0xbfb8aa3b, v48
	v_mul_f32_e32 v49, 0xbfb8aa3b, v49
	v_lshlrev_b32_e32 v77, 16, v67
	v_and_b32_e32 v67, 0xffff0000, v67
	v_lshlrev_b32_e32 v70, 16, v64
	v_and_b32_e32 v64, 0xffff0000, v64
	v_lshlrev_b32_e32 v71, 16, v65
	v_and_b32_e32 v65, 0xffff0000, v65
	v_lshlrev_b32_e32 v76, 16, v66
	v_and_b32_e32 v66, 0xffff0000, v66
	v_mul_f32_e32 v59, v59, v67
	v_mul_f32_e32 v60, v60, v70
	v_mul_f32_e32 v61, v61, v64
	v_mul_f32_e32 v62, v62, v71
	v_mul_f32_e32 v63, v63, v65
	v_mul_f32_e32 v64, v56, v76
	v_mul_f32_e32 v65, v57, v66
	v_mul_f32_e32 v66, v58, v77
	v_cvt_pk_bf16_f32 v56, v60, v61
	v_cvt_pk_bf16_f32 v57, v62, v63
	v_cvt_pk_bf16_f32 v58, v64, v65
	v_cvt_pk_bf16_f32 v59, v66, v59
	global_store_dwordx4 v68, v[56:59], s[26:27]
	s_waitcnt vmcnt(15)
;     __device__ __forceinline__ void operator()(const f32x4 (&acc)[2][2][4][2], const Unit& u, int wr, int wc, int fr, int fq, const EpiCtx& X) const {
;     ...
;         EPI_PIECES({ const unsigned goff = glo + (unsigned)(rl * W_SSM) * 2u, coff = clo + (unsigned)(rl * DM) * 2u;
;             GLU_ONE(p1a, p1b, goff, coff); GLU_ONE(p2a, p2b, goff + W_SSM * 2, coff + DM * 2); })
	s_nop 1
	v_mov_b32_e32 v56, v204
	v_mov_b32_e32 v57, v205
	v_mov_b32_e32 v58, v206
	v_mov_b32_e32 v59, v207
	v_mul_f32_e32 v50, 0xbfb8aa3b, v50
	v_exp_f32_e32 v51, v51
	v_exp_f32_e32 v52, v52
	v_exp_f32_e32 v53, v53
	v_exp_f32_e32 v54, v54
	v_exp_f32_e32 v55, v55
	v_exp_f32_e32 v48, v48
	v_exp_f32_e32 v49, v49
	v_exp_f32_e32 v50, v50
	v_add_f32_e32 v51, 1.0, v51
	v_add_f32_e32 v52, 1.0, v52
	v_add_f32_e32 v53, 1.0, v53
	v_add_f32_e32 v54, 1.0, v54
	v_add_f32_e32 v55, 1.0, v55
	v_add_f32_e32 v48, 1.0, v48
	v_add_f32_e32 v49, 1.0, v49
	v_add_f32_e32 v50, 1.0, v50
	v_rcp_f32_e32 v51, v51
	v_rcp_f32_e32 v52, v52
	v_rcp_f32_e32 v53, v53
	v_rcp_f32_e32 v54, v54
	v_rcp_f32_e32 v55, v55
	v_rcp_f32_e32 v48, v48
	v_rcp_f32_e32 v49, v49
	v_rcp_f32_e32 v50, v50
	v_add_u32_e32 v60, 0x102000, v150
	v_add_u32_e32 v61, 0x90000, v151
	v_mov_b32_e32 v67, 0
	v_mov_b32_e32 v66, 0
	v_lshlrev_b32_e32 v65, 16, v59
	v_and_b32_e32 v59, 0xffff0000, v59
	v_lshlrev_b32_e32 v62, 16, v56
	v_and_b32_e32 v56, 0xffff0000, v56
	v_lshlrev_b32_e32 v63, 16, v57
	v_and_b32_e32 v57, 0xffff0000, v57
	v_lshlrev_b32_e32 v64, 16, v58
	v_and_b32_e32 v58, 0xffff0000, v58
	v_mul_f32_e32 v51, v51, v59
	v_mul_f32_e32 v52, v52, v62
	v_mul_f32_e32 v53, v53, v56
	v_mul_f32_e32 v54, v54, v63
	v_mul_f32_e32 v55, v55, v57
	v_mul_f32_e32 v56, v48, v64
	v_mul_f32_e32 v57, v49, v58
	v_mul_f32_e32 v58, v50, v65
	v_cvt_pk_bf16_f32 v48, v52, v53
	v_cvt_pk_bf16_f32 v49, v54, v55
	v_cvt_pk_bf16_f32 v50, v56, v57
	v_cvt_pk_bf16_f32 v51, v58, v51
	global_store_dwordx4 v60, v[48:51], s[26:27]
	s_waitcnt vmcnt(15)
	s_nop 1
	v_mov_b32_e32 v48, v208
	v_mov_b32_e32 v49, v209
	v_mov_b32_e32 v50, v210
	v_mov_b32_e32 v51, v211
	v_cndmask_b32_e64 v60, v43, v35, s[6:7]
	v_cndmask_b32_e64 v52, v47, v39, s[6:7]
	v_cndmask_b32_e64 v53, v46, v38, s[6:7]
	v_cndmask_b32_e64 v54, v45, v37, s[6:7]
	v_cndmask_b32_e64 v55, v44, v36, s[6:7]
	v_mov_b32_e32 v56, 0
	v_mov_b32_e32 v57, 0
	v_mov_b32_e32 v58, 0
	v_mov_b32_e32 v59, 0
	v_cndmask_b32_e64 v61, v42, v34, s[6:7]
	v_cndmask_b32_e64 v62, v41, v33, s[6:7]
	v_cndmask_b32_e64 v63, v40, v32, s[6:7]
	v_mov_b32_e32 v64, 0
	v_mov_b32_e32 v65, 0
	v_mov_b32_dpp v67, v60 quad_perm:[1,0,3,2] row_mask:0xf bank_mask:0xf
	v_mov_b32_dpp v56, v55 quad_perm:[1,0,3,2] row_mask:0xf bank_mask:0xf
	v_mov_b32_dpp v57, v54 quad_perm:[1,0,3,2] row_mask:0xf bank_mask:0xf
	v_mov_b32_dpp v58, v53 quad_perm:[1,0,3,2] row_mask:0xf bank_mask:0xf
	v_mov_b32_dpp v59, v52 quad_perm:[1,0,3,2] row_mask:0xf bank_mask:0xf
	v_mov_b32_dpp v64, v63 quad_perm:[1,0,3,2] row_mask:0xf bank_mask:0xf
	v_mov_b32_dpp v65, v62 quad_perm:[1,0,3,2] row_mask:0xf bank_mask:0xf
	v_mov_b32_dpp v66, v61 quad_perm:[1,0,3,2] row_mask:0xf bank_mask:0xf
	v_cndmask_b32_e64 v43, v67, v43, s[6:7]
	v_cndmask_b32_e64 v47, v59, v47, s[6:7]
	v_cndmask_b32_e64 v46, v58, v46, s[6:7]
	v_cndmask_b32_e64 v45, v57, v45, s[6:7]
	v_cndmask_b32_e64 v44, v56, v44, s[6:7]
	v_cndmask_b32_e64 v42, v66, v42, s[6:7]
	v_cndmask_b32_e64 v41, v65, v41, s[6:7]
	v_cndmask_b32_e64 v40, v64, v40, s[6:7]
	v_mul_f32_e32 v43, 0xbfb8aa3b, v43
	v_mul_f32_e32 v44, 0xbfb8aa3b, v44
	v_mul_f32_e32 v45, 0xbfb8aa3b, v45
	v_mul_f32_e32 v46, 0xbfb8aa3b, v46
	v_mul_f32_e32 v47, 0xbfb8aa3b, v47
	v_mul_f32_e32 v40, 0xbfb8aa3b, v40
	v_mul_f32_e32 v41, 0xbfb8aa3b, v41
	v_mul_f32_e32 v42, 0xbfb8aa3b, v42
	v_exp_f32_e32 v43, v43
	v_exp_f32_e32 v44, v44
	v_exp_f32_e32 v45, v45
	v_exp_f32_e32 v46, v46
	v_exp_f32_e32 v47, v47
	v_exp_f32_e32 v40, v40
	v_exp_f32_e32 v41, v41
	v_exp_f32_e32 v42, v42
	v_add_f32_e32 v43, 1.0, v43
	v_add_f32_e32 v44, 1.0, v44
	v_add_f32_e32 v45, 1.0, v45
	v_add_f32_e32 v46, 1.0, v46
	v_add_f32_e32 v47, 1.0, v47
	v_add_f32_e32 v40, 1.0, v40
	v_add_f32_e32 v41, 1.0, v41
	v_add_f32_e32 v42, 1.0, v42
	v_rcp_f32_e32 v43, v43
	v_rcp_f32_e32 v44, v44
	v_rcp_f32_e32 v45, v45
	v_rcp_f32_e32 v46, v46
	v_rcp_f32_e32 v47, v47
	v_rcp_f32_e32 v40, v40
	v_rcp_f32_e32 v41, v41
	v_rcp_f32_e32 v42, v42
	v_add_u32_e32 v52, 0x120000, v150
	v_add_u32_e32 v53, 0x91000, v151
	v_cndmask_b32_e64 v35, v35, v67, s[6:7]
	v_cndmask_b32_e64 v39, v39, v59, s[6:7]
	v_cndmask_b32_e64 v38, v38, v58, s[6:7]
	v_cndmask_b32_e64 v37, v37, v57, s[6:7]
	v_cndmask_b32_e64 v36, v36, v56, s[6:7]
	v_cndmask_b32_e64 v34, v34, v66, s[6:7]
	v_cndmask_b32_e64 v33, v33, v65, s[6:7]
	v_cndmask_b32_e64 v32, v32, v64, s[6:7]
	v_mul_f32_e32 v35, 0xbfb8aa3b, v35
	v_mul_f32_e32 v36, 0xbfb8aa3b, v36
	v_mul_f32_e32 v37, 0xbfb8aa3b, v37
	v_mul_f32_e32 v38, 0xbfb8aa3b, v38
	v_mul_f32_e32 v39, 0xbfb8aa3b, v39
	v_mul_f32_e32 v32, 0xbfb8aa3b, v32
	v_mul_f32_e32 v33, 0xbfb8aa3b, v33
	v_lshlrev_b32_e32 v61, 16, v51
	v_and_b32_e32 v51, 0xffff0000, v51
	v_lshlrev_b32_e32 v54, 16, v48
	v_and_b32_e32 v48, 0xffff0000, v48
	v_lshlrev_b32_e32 v55, 16, v49
	v_and_b32_e32 v49, 0xffff0000, v49
	v_lshlrev_b32_e32 v60, 16, v50
	v_and_b32_e32 v50, 0xffff0000, v50
	v_mul_f32_e32 v43, v43, v51
	v_mul_f32_e32 v44, v44, v54
	v_mul_f32_e32 v45, v45, v48
	v_mul_f32_e32 v46, v46, v55
	v_mul_f32_e32 v47, v47, v49
	v_mul_f32_e32 v48, v40, v60
	v_mul_f32_e32 v49, v41, v50
	v_mul_f32_e32 v50, v42, v61
	v_cvt_pk_bf16_f32 v40, v44, v45
	v_cvt_pk_bf16_f32 v41, v46, v47
	v_cvt_pk_bf16_f32 v42, v48, v49
	v_cvt_pk_bf16_f32 v43, v50, v43
	global_store_dwordx4 v52, v[40:43], s[26:27]
	s_waitcnt vmcnt(15)
;     __device__ __forceinline__ void operator()(const f32x4 (&acc)[2][2][4][2], const Unit& u, int wr, int wc, int fr, int fq, const EpiCtx& X) const {
;     ...
;         EPI_PIECES({ const unsigned goff = glo + (unsigned)(rl * W_SSM) * 2u, coff = clo + (unsigned)(rl * DM) * 2u;
;             GLU_ONE(p1a, p1b, goff, coff); GLU_ONE(p2a, p2b, goff + W_SSM * 2, coff + DM * 2); })
	s_nop 1
	v_mov_b32_e32 v40, v220
	v_mov_b32_e32 v41, v221
	v_mov_b32_e32 v42, v222
	v_mov_b32_e32 v43, v223
	v_mul_f32_e32 v34, 0xbfb8aa3b, v34
	v_exp_f32_e32 v35, v35
	v_exp_f32_e32 v36, v36
	v_exp_f32_e32 v37, v37
	v_exp_f32_e32 v38, v38
	v_exp_f32_e32 v39, v39
	v_exp_f32_e32 v32, v32
	v_exp_f32_e32 v33, v33
	v_exp_f32_e32 v34, v34
	v_add_f32_e32 v35, 1.0, v35
	v_add_f32_e32 v36, 1.0, v36
	v_add_f32_e32 v37, 1.0, v37
	v_add_f32_e32 v38, 1.0, v38
	v_add_f32_e32 v39, 1.0, v39
	v_add_f32_e32 v32, 1.0, v32
	v_add_f32_e32 v33, 1.0, v33
	v_add_f32_e32 v34, 1.0, v34
	v_rcp_f32_e32 v35, v35
	v_rcp_f32_e32 v36, v36
	v_rcp_f32_e32 v37, v37
	v_rcp_f32_e32 v38, v38
	v_rcp_f32_e32 v39, v39
	v_rcp_f32_e32 v32, v32
	v_rcp_f32_e32 v33, v33
	v_rcp_f32_e32 v34, v34
	v_add_u32_e32 v44, 0x122000, v150
	v_add_u32_e32 v45, 0xa0000, v151
	v_mov_b32_e32 v51, 0
	v_mov_b32_e32 v50, 0
	v_lshlrev_b32_e32 v49, 16, v43
	v_and_b32_e32 v43, 0xffff0000, v43
	v_lshlrev_b32_e32 v46, 16, v40
	v_and_b32_e32 v40, 0xffff0000, v40
	v_lshlrev_b32_e32 v47, 16, v41
	v_and_b32_e32 v41, 0xffff0000, v41
	v_lshlrev_b32_e32 v48, 16, v42
	v_and_b32_e32 v42, 0xffff0000, v42
	v_mul_f32_e32 v35, v35, v43
	v_mul_f32_e32 v36, v36, v46
	v_mul_f32_e32 v37, v37, v40
	v_mul_f32_e32 v38, v38, v47
	v_mul_f32_e32 v39, v39, v41
	v_mul_f32_e32 v40, v32, v48
	v_mul_f32_e32 v41, v33, v42
	v_mul_f32_e32 v42, v34, v49
	v_cvt_pk_bf16_f32 v32, v36, v37
	v_cvt_pk_bf16_f32 v33, v38, v39
	v_cvt_pk_bf16_f32 v34, v40, v41
	v_cvt_pk_bf16_f32 v35, v42, v35
	global_store_dwordx4 v44, v[32:35], s[26:27]
	s_waitcnt vmcnt(15)
	s_nop 1
	v_mov_b32_e32 v32, v224
	v_mov_b32_e32 v33, v225
	v_mov_b32_e32 v34, v226
	v_mov_b32_e32 v35, v227
	v_cndmask_b32_e64 v44, v27, v19, s[6:7]
	v_cndmask_b32_e64 v36, v31, v23, s[6:7]
	v_cndmask_b32_e64 v37, v30, v22, s[6:7]
	v_cndmask_b32_e64 v38, v29, v21, s[6:7]
	v_cndmask_b32_e64 v39, v28, v20, s[6:7]
	v_mov_b32_e32 v40, 0
	v_mov_b32_e32 v41, 0
	v_mov_b32_e32 v42, 0
	v_mov_b32_e32 v43, 0
	v_cndmask_b32_e64 v45, v26, v18, s[6:7]
	v_cndmask_b32_e64 v46, v25, v17, s[6:7]
	v_cndmask_b32_e64 v47, v24, v16, s[6:7]
	v_mov_b32_e32 v48, 0
	v_mov_b32_e32 v49, 0
	v_mov_b32_dpp v51, v44 quad_perm:[1,0,3,2] row_mask:0xf bank_mask:0xf
	v_mov_b32_dpp v40, v39 quad_perm:[1,0,3,2] row_mask:0xf bank_mask:0xf
	v_mov_b32_dpp v41, v38 quad_perm:[1,0,3,2] row_mask:0xf bank_mask:0xf
	v_mov_b32_dpp v42, v37 quad_perm:[1,0,3,2] row_mask:0xf bank_mask:0xf
	v_mov_b32_dpp v43, v36 quad_perm:[1,0,3,2] row_mask:0xf bank_mask:0xf
	v_mov_b32_dpp v48, v47 quad_perm:[1,0,3,2] row_mask:0xf bank_mask:0xf
	v_mov_b32_dpp v49, v46 quad_perm:[1,0,3,2] row_mask:0xf bank_mask:0xf
	v_mov_b32_dpp v50, v45 quad_perm:[1,0,3,2] row_mask:0xf bank_mask:0xf
	v_cndmask_b32_e64 v27, v51, v27, s[6:7]
	v_cndmask_b32_e64 v31, v43, v31, s[6:7]
	v_cndmask_b32_e64 v30, v42, v30, s[6:7]
	v_cndmask_b32_e64 v29, v41, v29, s[6:7]
	v_cndmask_b32_e64 v28, v40, v28, s[6:7]
	v_cndmask_b32_e64 v26, v50, v26, s[6:7]
	v_cndmask_b32_e64 v25, v49, v25, s[6:7]
	v_cndmask_b32_e64 v24, v48, v24, s[6:7]
	v_mul_f32_e32 v27, 0xbfb8aa3b, v27
	v_mul_f32_e32 v28, 0xbfb8aa3b, v28
	v_mul_f32_e32 v29, 0xbfb8aa3b, v29
	v_mul_f32_e32 v30, 0xbfb8aa3b, v30
	v_mul_f32_e32 v31, 0xbfb8aa3b, v31
	v_mul_f32_e32 v24, 0xbfb8aa3b, v24
	v_mul_f32_e32 v25, 0xbfb8aa3b, v25
	v_mul_f32_e32 v26, 0xbfb8aa3b, v26
	v_exp_f32_e32 v27, v27
	v_exp_f32_e32 v28, v28
	v_exp_f32_e32 v29, v29
	v_exp_f32_e32 v30, v30
	v_exp_f32_e32 v31, v31
	v_exp_f32_e32 v24, v24
	v_exp_f32_e32 v25, v25
	v_exp_f32_e32 v26, v26
	v_add_f32_e32 v27, 1.0, v27
	v_add_f32_e32 v28, 1.0, v28
	v_add_f32_e32 v29, 1.0, v29
	v_add_f32_e32 v30, 1.0, v30
	v_add_f32_e32 v31, 1.0, v31
	v_add_f32_e32 v24, 1.0, v24
	v_add_f32_e32 v25, 1.0, v25
	v_add_f32_e32 v26, 1.0, v26
	v_rcp_f32_e32 v27, v27
	v_rcp_f32_e32 v28, v28
	v_rcp_f32_e32 v29, v29
	v_rcp_f32_e32 v30, v30
	v_rcp_f32_e32 v31, v31
	v_rcp_f32_e32 v24, v24
	v_rcp_f32_e32 v25, v25
	v_rcp_f32_e32 v26, v26
	v_add_u32_e32 v36, 0x140000, v150
	v_add_u32_e32 v37, 0xa1000, v151
	v_cndmask_b32_e64 v19, v19, v51, s[6:7]
	v_cndmask_b32_e64 v23, v23, v43, s[6:7]
	v_cndmask_b32_e64 v22, v22, v42, s[6:7]
	v_cndmask_b32_e64 v21, v21, v41, s[6:7]
	v_cndmask_b32_e64 v20, v20, v40, s[6:7]
	v_cndmask_b32_e64 v18, v18, v50, s[6:7]
	v_cndmask_b32_e64 v17, v17, v49, s[6:7]
	v_cndmask_b32_e64 v16, v16, v48, s[6:7]
	v_mul_f32_e32 v19, 0xbfb8aa3b, v19
	v_mul_f32_e32 v20, 0xbfb8aa3b, v20
	v_mul_f32_e32 v21, 0xbfb8aa3b, v21
	v_mul_f32_e32 v22, 0xbfb8aa3b, v22
	v_mul_f32_e32 v23, 0xbfb8aa3b, v23
	v_mul_f32_e32 v16, 0xbfb8aa3b, v16
	v_mul_f32_e32 v17, 0xbfb8aa3b, v17
	v_lshlrev_b32_e32 v45, 16, v35
	v_and_b32_e32 v35, 0xffff0000, v35
	v_lshlrev_b32_e32 v38, 16, v32
	v_and_b32_e32 v32, 0xffff0000, v32
	v_lshlrev_b32_e32 v39, 16, v33
	v_and_b32_e32 v33, 0xffff0000, v33
	v_lshlrev_b32_e32 v44, 16, v34
	v_and_b32_e32 v34, 0xffff0000, v34
	v_mul_f32_e32 v27, v27, v35
	v_mul_f32_e32 v28, v28, v38
	v_mul_f32_e32 v29, v29, v32
	v_mul_f32_e32 v30, v30, v39
	v_mul_f32_e32 v31, v31, v33
	v_mul_f32_e32 v32, v24, v44
	v_mul_f32_e32 v33, v25, v34
	v_mul_f32_e32 v34, v26, v45
	v_cvt_pk_bf16_f32 v24, v28, v29
	v_cvt_pk_bf16_f32 v25, v30, v31
	v_cvt_pk_bf16_f32 v26, v32, v33
	v_cvt_pk_bf16_f32 v27, v34, v27
	global_store_dwordx4 v36, v[24:27], s[26:27]
	s_waitcnt vmcnt(15)
;     __device__ __forceinline__ void operator()(const f32x4 (&acc)[2][2][4][2], const Unit& u, int wr, int wc, int fr, int fq, const EpiCtx& X) const {
;     ...
;         EPI_PIECES({ const unsigned goff = glo + (unsigned)(rl * W_SSM) * 2u, coff = clo + (unsigned)(rl * DM) * 2u;
;             GLU_ONE(p1a, p1b, goff, coff); GLU_ONE(p2a, p2b, goff + W_SSM * 2, coff + DM * 2); })
	s_nop 1
	v_mov_b32_e32 v24, v228
	v_mov_b32_e32 v25, v229
	v_mov_b32_e32 v26, v230
	v_mov_b32_e32 v27, v231
	v_mul_f32_e32 v18, 0xbfb8aa3b, v18
	v_exp_f32_e32 v19, v19
	v_exp_f32_e32 v20, v20
	v_exp_f32_e32 v21, v21
	v_exp_f32_e32 v22, v22
	v_exp_f32_e32 v23, v23
	v_exp_f32_e32 v16, v16
	v_exp_f32_e32 v17, v17
	v_exp_f32_e32 v18, v18
	v_add_f32_e32 v19, 1.0, v19
	v_add_f32_e32 v20, 1.0, v20
	v_add_f32_e32 v21, 1.0, v21
	v_add_f32_e32 v22, 1.0, v22
	v_add_f32_e32 v23, 1.0, v23
	v_add_f32_e32 v16, 1.0, v16
	v_add_f32_e32 v17, 1.0, v17
	v_add_f32_e32 v18, 1.0, v18
	v_rcp_f32_e32 v19, v19
	v_rcp_f32_e32 v20, v20
	v_rcp_f32_e32 v21, v21
	v_rcp_f32_e32 v22, v22
	v_rcp_f32_e32 v23, v23
	v_rcp_f32_e32 v16, v16
	v_rcp_f32_e32 v17, v17
	v_rcp_f32_e32 v18, v18
	v_add_u32_e32 v28, 0x142000, v150
	v_add_u32_e32 v29, 0xb0000, v151
	v_mov_b32_e32 v35, 0
	v_mov_b32_e32 v34, 0
	v_lshlrev_b32_e32 v33, 16, v27
	v_and_b32_e32 v27, 0xffff0000, v27
	v_lshlrev_b32_e32 v30, 16, v24
	v_and_b32_e32 v24, 0xffff0000, v24
	v_lshlrev_b32_e32 v31, 16, v25
	v_and_b32_e32 v25, 0xffff0000, v25
	v_lshlrev_b32_e32 v32, 16, v26
	v_and_b32_e32 v26, 0xffff0000, v26
	v_mul_f32_e32 v19, v19, v27
	v_mul_f32_e32 v20, v20, v30
	v_mul_f32_e32 v21, v21, v24
	v_mul_f32_e32 v22, v22, v31
	v_mul_f32_e32 v23, v23, v25
	v_mul_f32_e32 v24, v16, v32
	v_mul_f32_e32 v25, v17, v26
	v_mul_f32_e32 v26, v18, v33
	v_cvt_pk_bf16_f32 v16, v20, v21
	v_cvt_pk_bf16_f32 v17, v22, v23
	v_cvt_pk_bf16_f32 v18, v24, v25
	v_cvt_pk_bf16_f32 v19, v26, v19
	global_store_dwordx4 v28, v[16:19], s[26:27]
	s_waitcnt vmcnt(15)
	s_nop 1
	v_mov_b32_e32 v16, v232
	v_mov_b32_e32 v17, v233
	v_mov_b32_e32 v18, v234
	v_mov_b32_e32 v19, v235
	v_cndmask_b32_e64 v28, v11, v3, s[6:7]
	v_cndmask_b32_e64 v20, v15, v7, s[6:7]
	v_cndmask_b32_e64 v21, v14, v6, s[6:7]
	v_cndmask_b32_e64 v22, v13, v5, s[6:7]
	v_cndmask_b32_e64 v23, v12, v4, s[6:7]
	v_mov_b32_e32 v24, 0
	v_mov_b32_e32 v25, 0
	v_mov_b32_e32 v26, 0
	v_mov_b32_e32 v27, 0
	v_cndmask_b32_e64 v29, v10, v2, s[6:7]
	v_cndmask_b32_e64 v30, v9, v1, s[6:7]
	v_cndmask_b32_e64 v31, v8, v0, s[6:7]
	v_mov_b32_e32 v32, 0
	v_mov_b32_e32 v33, 0
	v_mov_b32_dpp v35, v28 quad_perm:[1,0,3,2] row_mask:0xf bank_mask:0xf
	v_mov_b32_dpp v24, v23 quad_perm:[1,0,3,2] row_mask:0xf bank_mask:0xf
	v_mov_b32_dpp v25, v22 quad_perm:[1,0,3,2] row_mask:0xf bank_mask:0xf
	v_mov_b32_dpp v26, v21 quad_perm:[1,0,3,2] row_mask:0xf bank_mask:0xf
	v_mov_b32_dpp v27, v20 quad_perm:[1,0,3,2] row_mask:0xf bank_mask:0xf
	v_mov_b32_dpp v32, v31 quad_perm:[1,0,3,2] row_mask:0xf bank_mask:0xf
	v_mov_b32_dpp v33, v30 quad_perm:[1,0,3,2] row_mask:0xf bank_mask:0xf
	v_mov_b32_dpp v34, v29 quad_perm:[1,0,3,2] row_mask:0xf bank_mask:0xf
	v_cndmask_b32_e64 v11, v35, v11, s[6:7]
	v_cndmask_b32_e64 v15, v27, v15, s[6:7]
	v_cndmask_b32_e64 v14, v26, v14, s[6:7]
	v_cndmask_b32_e64 v13, v25, v13, s[6:7]
	v_cndmask_b32_e64 v12, v24, v12, s[6:7]
	v_cndmask_b32_e64 v10, v34, v10, s[6:7]
	v_cndmask_b32_e64 v9, v33, v9, s[6:7]
	v_cndmask_b32_e64 v8, v32, v8, s[6:7]
	v_mul_f32_e32 v11, 0xbfb8aa3b, v11
	v_mul_f32_e32 v12, 0xbfb8aa3b, v12
	v_mul_f32_e32 v13, 0xbfb8aa3b, v13
	v_mul_f32_e32 v14, 0xbfb8aa3b, v14
	v_mul_f32_e32 v15, 0xbfb8aa3b, v15
	v_mul_f32_e32 v8, 0xbfb8aa3b, v8
	v_mul_f32_e32 v9, 0xbfb8aa3b, v9
	v_mul_f32_e32 v10, 0xbfb8aa3b, v10
	v_exp_f32_e32 v11, v11
	v_exp_f32_e32 v12, v12
	v_exp_f32_e32 v13, v13
	v_exp_f32_e32 v14, v14
	v_exp_f32_e32 v15, v15
	v_exp_f32_e32 v8, v8
	v_exp_f32_e32 v9, v9
	v_exp_f32_e32 v10, v10
	v_add_f32_e32 v11, 1.0, v11
	v_add_f32_e32 v12, 1.0, v12
	v_add_f32_e32 v13, 1.0, v13
	v_add_f32_e32 v14, 1.0, v14
	v_add_f32_e32 v15, 1.0, v15
	v_add_f32_e32 v8, 1.0, v8
	v_add_f32_e32 v9, 1.0, v9
	v_add_f32_e32 v10, 1.0, v10
	v_rcp_f32_e32 v11, v11
	v_rcp_f32_e32 v12, v12
	v_rcp_f32_e32 v13, v13
	v_rcp_f32_e32 v14, v14
	v_rcp_f32_e32 v15, v15
	v_rcp_f32_e32 v8, v8
	v_rcp_f32_e32 v9, v9
	v_rcp_f32_e32 v10, v10
	v_add_u32_e32 v20, 0x160000, v150
	v_add_u32_e32 v21, 0xb1000, v151
	v_cndmask_b32_e64 v3, v3, v35, s[6:7]
	v_cndmask_b32_e64 v7, v7, v27, s[6:7]
	v_cndmask_b32_e64 v6, v6, v26, s[6:7]
	v_cndmask_b32_e64 v5, v5, v25, s[6:7]
	v_cndmask_b32_e64 v4, v4, v24, s[6:7]
	v_cndmask_b32_e64 v2, v2, v34, s[6:7]
	v_cndmask_b32_e64 v1, v1, v33, s[6:7]
	v_cndmask_b32_e64 v0, v0, v32, s[6:7]
	v_mul_f32_e32 v3, 0xbfb8aa3b, v3
	v_mul_f32_e32 v4, 0xbfb8aa3b, v4
	v_mul_f32_e32 v5, 0xbfb8aa3b, v5
	v_mul_f32_e32 v6, 0xbfb8aa3b, v6
	v_mul_f32_e32 v7, 0xbfb8aa3b, v7
	v_mul_f32_e32 v0, 0xbfb8aa3b, v0
	v_mul_f32_e32 v1, 0xbfb8aa3b, v1
	v_lshlrev_b32_e32 v29, 16, v19
	v_and_b32_e32 v19, 0xffff0000, v19
	v_lshlrev_b32_e32 v22, 16, v16
	v_and_b32_e32 v16, 0xffff0000, v16
	v_lshlrev_b32_e32 v23, 16, v17
	v_and_b32_e32 v17, 0xffff0000, v17
	v_lshlrev_b32_e32 v28, 16, v18
	v_and_b32_e32 v18, 0xffff0000, v18
	v_mul_f32_e32 v11, v11, v19
	v_mul_f32_e32 v12, v12, v22
	v_mul_f32_e32 v13, v13, v16
	v_mul_f32_e32 v14, v14, v23
	v_mul_f32_e32 v15, v15, v17
	v_mul_f32_e32 v16, v8, v28
	v_mul_f32_e32 v17, v9, v18
	v_mul_f32_e32 v18, v10, v29
	v_cvt_pk_bf16_f32 v8, v12, v13
	v_cvt_pk_bf16_f32 v9, v14, v15
	v_cvt_pk_bf16_f32 v10, v16, v17
	v_cvt_pk_bf16_f32 v11, v18, v11
	global_store_dwordx4 v20, v[8:11], s[26:27]
	s_waitcnt vmcnt(15)
	s_nop 1
	v_mov_b32_e32 v8, v236
	v_mov_b32_e32 v9, v237
	v_mov_b32_e32 v10, v238
	v_mov_b32_e32 v11, v239
	v_mul_f32_e32 v2, 0xbfb8aa3b, v2
	v_exp_f32_e32 v3, v3
	v_exp_f32_e32 v4, v4
	v_exp_f32_e32 v5, v5
	v_exp_f32_e32 v6, v6
	v_exp_f32_e32 v7, v7
	v_exp_f32_e32 v0, v0
	v_exp_f32_e32 v1, v1
	v_exp_f32_e32 v2, v2
	v_add_f32_e32 v3, 1.0, v3
	v_add_f32_e32 v4, 1.0, v4
	v_add_f32_e32 v5, 1.0, v5
	v_add_f32_e32 v6, 1.0, v6
	v_add_f32_e32 v7, 1.0, v7
	v_add_f32_e32 v0, 1.0, v0
	v_add_f32_e32 v1, 1.0, v1
	v_add_f32_e32 v2, 1.0, v2
	v_rcp_f32_e32 v3, v3
	v_rcp_f32_e32 v4, v4
	v_rcp_f32_e32 v5, v5
	v_rcp_f32_e32 v6, v6
	v_rcp_f32_e32 v7, v7
	v_rcp_f32_e32 v0, v0
	v_rcp_f32_e32 v1, v1
	v_rcp_f32_e32 v2, v2
	v_add_u32_e32 v12, 0x162000, v150
	v_lshlrev_b32_e32 v16, 16, v11
	v_and_b32_e32 v11, 0xffff0000, v11
	v_lshlrev_b32_e32 v13, 16, v8
	v_and_b32_e32 v8, 0xffff0000, v8
	v_lshlrev_b32_e32 v14, 16, v9
	v_and_b32_e32 v9, 0xffff0000, v9
	v_lshlrev_b32_e32 v15, 16, v10
	v_and_b32_e32 v10, 0xffff0000, v10
	v_mul_f32_e32 v3, v3, v11
	v_mul_f32_e32 v4, v4, v13
	v_mul_f32_e32 v5, v5, v8
	v_mul_f32_e32 v6, v6, v14
	v_mul_f32_e32 v7, v7, v9
	v_mul_f32_e32 v8, v0, v15
	v_mul_f32_e32 v9, v1, v10
	v_mul_f32_e32 v10, v2, v16
	v_cvt_pk_bf16_f32 v0, v4, v5
	v_cvt_pk_bf16_f32 v1, v6, v7
	v_cvt_pk_bf16_f32 v2, v8, v9
	v_cvt_pk_bf16_f32 v3, v10, v3
	global_store_dwordx4 v12, v[0:3], s[26:27]
	s_cbranch_vccnz .LBB0_491
	s_and_b64 vcc, exec, s[4:5]
	s_cbranch_vccnz .LBB0_490
	s_barrier
	s_branch .LBB0_490
